# grid barrier seams 2-9 rewritten: non-returning arrival atomic, one designated workgroup per XCD polls the XCD counter then wbl2 + cross-XCD arrival, everyone polls the cross-XCD arrival counter; firs
# speedup vs baseline: 1.0031x; 1.0017x over previous
; __device__ __forceinline__ unsigned xb_ld(unsigned* p)              { return __hip_atomic_load(p, __ATOMIC_RELAXED, __HIP_MEMORY_SCOPE_AGENT); }
; __device__ __forceinline__ unsigned xb_add(unsigned* p, unsigned v) { return __hip_atomic_fetch_add(p, v, __ATOMIC_RELAXED, __HIP_MEMORY_SCOPE_AGENT); }
; #define XB_SPIN(cond, bar) do { unsigned _sp = 0; while (cond) { __builtin_amdgcn_s_sleep(1); \
;     if ((++_sp & 255u) == 0u) { if (xb_ld(&(bar)[XB_TMO])) break; if (_sp > XB_SPIN_CAP) { atomicAdd(&(bar)[XB_TMO], 1u); break; } } } } while (0)
; __device__ __forceinline__ void xcd_barrier(const XcdBarrier& b, const int wid) {
;     ...
;         const unsigned old = xb_add(&bar[XB_XSUB(b.x)], 1u);
;         const unsigned gen = old / nloc;
;         if (old + 1u == (gen + 1u) * nloc) {
;             __builtin_amdgcn_fence(__ATOMIC_RELEASE, "agent");
;             asm volatile("s_waitcnt vmcnt(0)" ::: "memory");
;             const unsigned og = xb_add(&bar[XB_TOP], 1u);
;             const unsigned tg = og / nx;
;             if (og + 1u == (tg + 1u) * nx) xb_add(&bar[XB_TOPGEN], 1u);
;             else XB_SPIN(xb_ld(&bar[XB_TOPGEN]) == tg, bar);
;             __builtin_amdgcn_fence(__ATOMIC_ACQUIRE, "agent");
;             xb_add(&bar[XB_XGEN(b.x)], 1u);
.LBB0_239:
	s_andn2_saveexec_b64 s[4:5], s[4:5]
	s_cbranch_execz .LBB0_257
	s_mov_b64 s[4:5], exec
	v_readlane_b32 s8, v254, 9
	s_nop 3
	v_mov_b32_e32 v6, s8
	v_mov_b32_e32 v7, 1
	ds_write_b32 v6, v7 offset:12
	buffer_wbl2 sc1
	s_waitcnt lgkmcnt(0)
	s_waitcnt vmcnt(0)
	v_mbcnt_lo_u32_b32 v1, s4, 0
	v_mbcnt_hi_u32_b32 v1, s5, v1
	v_cmp_eq_u32_e32 vcc, 0, v1
	s_and_saveexec_b64 s[6:7], vcc
	s_cbranch_execz .LBB0_242
	s_bcnt1_i32_b64 s4, s[4:5]
	v_mov_b32_e32 v2, 0x7000
	v_mov_b32_e32 v3, s4
	global_atomic_add v2, v2, v3, s[86:87] offset:1024 sc0

; __device__ __forceinline__ int lane_id_asm() { int l; asm volatile("v_mbcnt_lo_u32_b32 %0, -1, 0\n\tv_mbcnt_hi_u32_b32 %0, -1, %0" : "=v"(l)); return l; }
; __device__ __forceinline__ unsigned xb_ld(unsigned* p)              { return __hip_atomic_load(p, __ATOMIC_RELAXED, __HIP_MEMORY_SCOPE_AGENT); }
; __device__ __forceinline__ unsigned xb_add(unsigned* p, unsigned v) { return __hip_atomic_fetch_add(p, v, __ATOMIC_RELAXED, __HIP_MEMORY_SCOPE_AGENT); }
; #define XB_SPIN(cond, bar) do { unsigned _sp = 0; while (cond) { __builtin_amdgcn_s_sleep(1); \
;     if ((++_sp & 255u) == 0u) { if (xb_ld(&(bar)[XB_TMO])) break; if (_sp > XB_SPIN_CAP) { atomicAdd(&(bar)[XB_TMO], 1u); break; } } } } while (0)
; __device__ __forceinline__ void xcd_barrier(const XcdBarrier& b, const int wid) {
;     asm volatile("s_waitcnt vmcnt(0)" ::: "memory");
;     __syncthreads();
;     if (wid == 0 && lane_id_asm() == 0) {
;         unsigned* bar = b.bar;
;         __builtin_amdgcn_s_waitcnt(0);
;         unsigned nloc = b.st[0], nx = b.st[1];
;         if (nloc == 0u) { xcd_barrier_complete(bar, b.x, nloc, nx); b.st[0] = nloc; b.st[1] = nx; }
;         const unsigned old = xb_add(&bar[XB_XSUB(b.x)], 1u);
;         const unsigned gen = old / nloc;
;         if (old + 1u == (gen + 1u) * nloc) {
;             __builtin_amdgcn_fence(__ATOMIC_RELEASE, "agent");
;             asm volatile("s_waitcnt vmcnt(0)" ::: "memory");
;             const unsigned og = xb_add(&bar[XB_TOP], 1u);
;             const unsigned tg = og / nx;
;             if (og + 1u == (tg + 1u) * nx) xb_add(&bar[XB_TOPGEN], 1u);
;             else XB_SPIN(xb_ld(&bar[XB_TOPGEN]) == tg, bar);
;             __builtin_amdgcn_fence(__ATOMIC_ACQUIRE, "agent");
;             xb_add(&bar[XB_XGEN(b.x)], 1u);
;             asm volatile("s_waitcnt vmcnt(0)" ::: "memory");
;         } else {
;             XB_SPIN(xb_ld(&bar[XB_XGEN(b.x)]) == gen, bar);
;             __builtin_amdgcn_fence(__ATOMIC_ACQUIRE, "agent");
;             asm volatile("s_waitcnt vmcnt(0)" ::: "memory");
;         }
;     }
;     __syncthreads();
.LBB0_686:
	v_readlane_b32 s0, v254, 13
	v_readlane_b32 s1, v254, 14
	s_and_b64 vcc, exec, s[0:1]
	s_cbranch_vccnz .LBB0_738
	s_waitcnt vmcnt(0)
	s_cmp_gt_u32 s79, 63
	s_waitcnt vmcnt(0) lgkmcnt(0)
	s_barrier
	s_cbranch_scc1 .LBB0_737
	v_mbcnt_lo_u32_b32 v0, -1, 0
	v_mbcnt_hi_u32_b32 v0, -1, v0
	s_nop 0
	v_cmp_eq_u32_e32 vcc, 0, v0
	s_and_saveexec_b64 s[0:1], vcc
	s_cbranch_execz .LBB0_736
	v_readlane_b32 s2, v254, 9
	s_waitcnt vmcnt(0) expcnt(0) lgkmcnt(0)
	s_nop 0
	v_mov_b32_e32 v0, s2
	ds_read_b32 v2, v0
	ds_read_b32 v3, v0 offset:4
	ds_read_b32 v4, v0 offset:8
	ds_read_b32 v5, v0 offset:12
	v_readlane_b32 s2, v254, 8
	s_lshl_b32 s2, s2, 8
	v_readlane_b32 s4, v254, 6
	v_readlane_b32 s5, v254, 7
	s_add_u32 s2, s4, s2
	s_addc_u32 s3, s5, 0
	v_mov_b32_e32 v1, 0x1000
	v_mov_b32_e32 v6, 1
	global_atomic_add v1, v6, s[2:3] offset:1024
	s_waitcnt lgkmcnt(0)
	v_add_u32_e32 v6, 1, v4
	ds_write_b32 v0, v6 offset:8
	v_add_u32_e32 v4, 2, v4
	v_mul_lo_u32 v2, v2, v4
	v_mul_lo_u32 v3, v3, v4
	s_add_u32 s10, s86, 0x7400
	s_addc_u32 s11, s87, 0
	s_mov_b32 s4, 0x200000
	v_cmp_eq_u32_e32 vcc, 0, v5
	s_cbranch_vccnz .Lxb2_wait
.Lxb2_l:
	global_load_dword v6, v1, s[2:3] offset:1024 sc1
	s_sub_i32 s4, s4, 1
	s_waitcnt vmcnt(0)
	v_cmp_ge_u32_e32 vcc, v6, v2
	s_cbranch_vccnz .Lxb2_go
	s_cmp_eq_u32 s4, 0
	s_cbranch_scc1 .Lxb2_go
	s_sleep 1
	s_branch .Lxb2_l
.Lxb2_go:
	buffer_wbl2 sc1
	s_waitcnt vmcnt(0)
	v_mov_b32_e32 v6, 0x7000
	v_mov_b32_e32 v7, 1
	global_atomic_add v6, v7, s[86:87] offset:1024
.Lxb2_wait:
	v_mov_b32_e32 v0, 0
.Lxb2_w:
	global_load_dword v6, v0, s[10:11] sc1
	s_sub_i32 s4, s4, 1
	s_waitcnt vmcnt(0)
	v_cmp_ge_u32_e32 vcc, v6, v3
	s_cbranch_vccnz .Lxb2_acq
	s_cmp_eq_u32 s4, 0
	s_cbranch_scc1 .Lxb2_acq
	s_sleep 1
	s_branch .Lxb2_w
.Lxb2_acq:
	buffer_inv sc1
	s_waitcnt vmcnt(0)

; __device__ __forceinline__ int lane_id_asm() { int l; asm volatile("v_mbcnt_lo_u32_b32 %0, -1, 0\n\tv_mbcnt_hi_u32_b32 %0, -1, %0" : "=v"(l)); return l; }
; __device__ __forceinline__ unsigned xb_ld(unsigned* p)              { return __hip_atomic_load(p, __ATOMIC_RELAXED, __HIP_MEMORY_SCOPE_AGENT); }
; __device__ __forceinline__ unsigned xb_add(unsigned* p, unsigned v) { return __hip_atomic_fetch_add(p, v, __ATOMIC_RELAXED, __HIP_MEMORY_SCOPE_AGENT); }
; #define XB_SPIN(cond, bar) do { unsigned _sp = 0; while (cond) { __builtin_amdgcn_s_sleep(1); \
;     if ((++_sp & 255u) == 0u) { if (xb_ld(&(bar)[XB_TMO])) break; if (_sp > XB_SPIN_CAP) { atomicAdd(&(bar)[XB_TMO], 1u); break; } } } } while (0)
; __device__ __forceinline__ void xcd_barrier(const XcdBarrier& b, const int wid) {
;     asm volatile("s_waitcnt vmcnt(0)" ::: "memory");
;     __syncthreads();
;     if (wid == 0 && lane_id_asm() == 0) {
;         unsigned* bar = b.bar;
;         __builtin_amdgcn_s_waitcnt(0);
;         unsigned nloc = b.st[0], nx = b.st[1];
;         if (nloc == 0u) { xcd_barrier_complete(bar, b.x, nloc, nx); b.st[0] = nloc; b.st[1] = nx; }
;         const unsigned old = xb_add(&bar[XB_XSUB(b.x)], 1u);
;         const unsigned gen = old / nloc;
;         if (old + 1u == (gen + 1u) * nloc) {
;             __builtin_amdgcn_fence(__ATOMIC_RELEASE, "agent");
;             asm volatile("s_waitcnt vmcnt(0)" ::: "memory");
;             const unsigned og = xb_add(&bar[XB_TOP], 1u);
;             const unsigned tg = og / nx;
;             if (og + 1u == (tg + 1u) * nx) xb_add(&bar[XB_TOPGEN], 1u);
;             else XB_SPIN(xb_ld(&bar[XB_TOPGEN]) == tg, bar);
;             __builtin_amdgcn_fence(__ATOMIC_ACQUIRE, "agent");
;             xb_add(&bar[XB_XGEN(b.x)], 1u);
;             asm volatile("s_waitcnt vmcnt(0)" ::: "memory");
;         } else {
;             XB_SPIN(xb_ld(&bar[XB_XGEN(b.x)]) == gen, bar);
;             __builtin_amdgcn_fence(__ATOMIC_ACQUIRE, "agent");
;             asm volatile("s_waitcnt vmcnt(0)" ::: "memory");
;         }
;     }
;     __syncthreads();
.LBB0_820:
	v_readlane_b32 s0, v254, 13
	v_readlane_b32 s1, v254, 14
	s_and_b64 vcc, exec, s[0:1]
	s_cbranch_vccnz .LBB0_872
	s_waitcnt vmcnt(0)
	s_cmp_gt_u32 s79, 63
	s_waitcnt vmcnt(0)
	s_barrier
	s_cbranch_scc1 .LBB0_871
	v_mbcnt_lo_u32_b32 v0, -1, 0
	v_mbcnt_hi_u32_b32 v0, -1, v0
	s_nop 0
	v_cmp_eq_u32_e32 vcc, 0, v0
	s_and_saveexec_b64 s[0:1], vcc
	s_cbranch_execz .LBB0_870
	v_readlane_b32 s2, v254, 9
	s_waitcnt vmcnt(0) expcnt(0) lgkmcnt(0)
	s_nop 0
	v_mov_b32_e32 v0, s2
	ds_read_b32 v2, v0
	ds_read_b32 v3, v0 offset:4
	ds_read_b32 v4, v0 offset:8
	ds_read_b32 v5, v0 offset:12
	v_readlane_b32 s2, v254, 8
	s_lshl_b32 s2, s2, 8
	v_readlane_b32 s4, v254, 6
	v_readlane_b32 s5, v254, 7
	s_add_u32 s2, s4, s2
	s_addc_u32 s3, s5, 0
	v_mov_b32_e32 v1, 0x1000
	v_mov_b32_e32 v6, 1
	global_atomic_add v1, v6, s[2:3] offset:1024
	s_waitcnt lgkmcnt(0)
	v_add_u32_e32 v6, 1, v4
	ds_write_b32 v0, v6 offset:8
	v_add_u32_e32 v4, 2, v4
	v_mul_lo_u32 v2, v2, v4
	v_mul_lo_u32 v3, v3, v4
	s_add_u32 s10, s86, 0x7400
	s_addc_u32 s11, s87, 0
	s_mov_b32 s4, 0x200000
	v_cmp_eq_u32_e32 vcc, 0, v5
	s_cbranch_vccnz .Lxb3_wait

; __device__ __forceinline__ int lane_id_asm() { int l; asm volatile("v_mbcnt_lo_u32_b32 %0, -1, 0\n\tv_mbcnt_hi_u32_b32 %0, -1, %0" : "=v"(l)); return l; }
; __device__ __forceinline__ unsigned xb_ld(unsigned* p)              { return __hip_atomic_load(p, __ATOMIC_RELAXED, __HIP_MEMORY_SCOPE_AGENT); }
; __device__ __forceinline__ unsigned xb_add(unsigned* p, unsigned v) { return __hip_atomic_fetch_add(p, v, __ATOMIC_RELAXED, __HIP_MEMORY_SCOPE_AGENT); }
; #define XB_SPIN(cond, bar) do { unsigned _sp = 0; while (cond) { __builtin_amdgcn_s_sleep(1); \
;     if ((++_sp & 255u) == 0u) { if (xb_ld(&(bar)[XB_TMO])) break; if (_sp > XB_SPIN_CAP) { atomicAdd(&(bar)[XB_TMO], 1u); break; } } } } while (0)
; __device__ __forceinline__ void xcd_barrier(const XcdBarrier& b, const int wid) {
;     asm volatile("s_waitcnt vmcnt(0)" ::: "memory");
;     __syncthreads();
;     if (wid == 0 && lane_id_asm() == 0) {
;         unsigned* bar = b.bar;
;         __builtin_amdgcn_s_waitcnt(0);
;         unsigned nloc = b.st[0], nx = b.st[1];
;         if (nloc == 0u) { xcd_barrier_complete(bar, b.x, nloc, nx); b.st[0] = nloc; b.st[1] = nx; }
;         const unsigned old = xb_add(&bar[XB_XSUB(b.x)], 1u);
;         const unsigned gen = old / nloc;
;         if (old + 1u == (gen + 1u) * nloc) {
;             __builtin_amdgcn_fence(__ATOMIC_RELEASE, "agent");
;             asm volatile("s_waitcnt vmcnt(0)" ::: "memory");
;             const unsigned og = xb_add(&bar[XB_TOP], 1u);
;             const unsigned tg = og / nx;
;             if (og + 1u == (tg + 1u) * nx) xb_add(&bar[XB_TOPGEN], 1u);
;             else XB_SPIN(xb_ld(&bar[XB_TOPGEN]) == tg, bar);
;             __builtin_amdgcn_fence(__ATOMIC_ACQUIRE, "agent");
;             xb_add(&bar[XB_XGEN(b.x)], 1u);
;             asm volatile("s_waitcnt vmcnt(0)" ::: "memory");
;         } else {
;             XB_SPIN(xb_ld(&bar[XB_XGEN(b.x)]) == gen, bar);
;             __builtin_amdgcn_fence(__ATOMIC_ACQUIRE, "agent");
;             asm volatile("s_waitcnt vmcnt(0)" ::: "memory");
;         }
;     }
;     __syncthreads();
.LBB0_1476:
	s_and_b64 vcc, exec, s[60:61]
	s_cbranch_vccnz .LBB0_1528
	s_waitcnt vmcnt(0)
	s_cmp_gt_u32 s79, 63
	s_waitcnt vmcnt(0) lgkmcnt(0)
	s_barrier
	s_cbranch_scc1 .LBB0_1527
	v_mbcnt_lo_u32_b32 v0, -1, 0
	v_mbcnt_hi_u32_b32 v0, -1, v0
	s_nop 0
	v_cmp_eq_u32_e32 vcc, 0, v0
	s_and_saveexec_b64 s[0:1], vcc
	s_cbranch_execz .LBB0_1526
	v_readlane_b32 s2, v254, 9
	s_waitcnt vmcnt(0) expcnt(0) lgkmcnt(0)
	s_nop 0
	v_mov_b32_e32 v0, s2
	ds_read_b32 v2, v0
	ds_read_b32 v3, v0 offset:4
	ds_read_b32 v4, v0 offset:8
	ds_read_b32 v5, v0 offset:12
	v_readlane_b32 s2, v254, 8
	s_lshl_b32 s2, s2, 8
	v_readlane_b32 s4, v254, 6
	v_readlane_b32 s5, v254, 7
	s_add_u32 s2, s4, s2
	s_addc_u32 s3, s5, 0
	v_mov_b32_e32 v1, 0x1000
	v_mov_b32_e32 v6, 1
	global_atomic_add v1, v6, s[2:3] offset:1024
	s_waitcnt lgkmcnt(0)
	v_add_u32_e32 v6, 1, v4
	ds_write_b32 v0, v6 offset:8
	v_add_u32_e32 v4, 2, v4
	v_mul_lo_u32 v2, v2, v4
	v_mul_lo_u32 v3, v3, v4
	s_add_u32 s10, s86, 0x7400
	s_addc_u32 s11, s87, 0
	s_mov_b32 s4, 0x200000
	v_cmp_eq_u32_e32 vcc, 0, v5
	s_cbranch_vccnz .Lxb5_wait

; __device__ __forceinline__ int lane_id_asm() { int l; asm volatile("v_mbcnt_lo_u32_b32 %0, -1, 0\n\tv_mbcnt_hi_u32_b32 %0, -1, %0" : "=v"(l)); return l; }
; __device__ __forceinline__ unsigned xb_ld(unsigned* p)              { return __hip_atomic_load(p, __ATOMIC_RELAXED, __HIP_MEMORY_SCOPE_AGENT); }
; __device__ __forceinline__ unsigned xb_add(unsigned* p, unsigned v) { return __hip_atomic_fetch_add(p, v, __ATOMIC_RELAXED, __HIP_MEMORY_SCOPE_AGENT); }
; #define XB_SPIN(cond, bar) do { unsigned _sp = 0; while (cond) { __builtin_amdgcn_s_sleep(1); \
;     if ((++_sp & 255u) == 0u) { if (xb_ld(&(bar)[XB_TMO])) break; if (_sp > XB_SPIN_CAP) { atomicAdd(&(bar)[XB_TMO], 1u); break; } } } } while (0)
; __device__ __forceinline__ void xcd_barrier(const XcdBarrier& b, const int wid) {
;     asm volatile("s_waitcnt vmcnt(0)" ::: "memory");
;     __syncthreads();
;     if (wid == 0 && lane_id_asm() == 0) {
;         unsigned* bar = b.bar;
;         __builtin_amdgcn_s_waitcnt(0);
;         unsigned nloc = b.st[0], nx = b.st[1];
;         if (nloc == 0u) { xcd_barrier_complete(bar, b.x, nloc, nx); b.st[0] = nloc; b.st[1] = nx; }
;         const unsigned old = xb_add(&bar[XB_XSUB(b.x)], 1u);
;         const unsigned gen = old / nloc;
;         if (old + 1u == (gen + 1u) * nloc) {
;             __builtin_amdgcn_fence(__ATOMIC_RELEASE, "agent");
;             asm volatile("s_waitcnt vmcnt(0)" ::: "memory");
;             const unsigned og = xb_add(&bar[XB_TOP], 1u);
;             const unsigned tg = og / nx;
;             if (og + 1u == (tg + 1u) * nx) xb_add(&bar[XB_TOPGEN], 1u);
;             else XB_SPIN(xb_ld(&bar[XB_TOPGEN]) == tg, bar);
;             __builtin_amdgcn_fence(__ATOMIC_ACQUIRE, "agent");
;             xb_add(&bar[XB_XGEN(b.x)], 1u);
;             asm volatile("s_waitcnt vmcnt(0)" ::: "memory");
;         } else {
;             XB_SPIN(xb_ld(&bar[XB_XGEN(b.x)]) == gen, bar);
;             __builtin_amdgcn_fence(__ATOMIC_ACQUIRE, "agent");
;             asm volatile("s_waitcnt vmcnt(0)" ::: "memory");
;         }
;     }
;     __syncthreads();
.LBB0_1621:
	s_and_b64 vcc, exec, s[60:61]
	s_cbranch_vccnz .LBB0_1673
	s_waitcnt vmcnt(0)
	s_cmp_gt_u32 s79, 63
	s_waitcnt vmcnt(0)
	s_barrier
	s_cbranch_scc1 .LBB0_1672
	v_mbcnt_lo_u32_b32 v0, -1, 0
	v_mbcnt_hi_u32_b32 v0, -1, v0
	s_nop 0
	v_cmp_eq_u32_e32 vcc, 0, v0
	s_and_saveexec_b64 s[0:1], vcc
	s_cbranch_execz .LBB0_1671
	v_readlane_b32 s2, v254, 9
	s_waitcnt vmcnt(0) expcnt(0) lgkmcnt(0)
	s_nop 0
	v_mov_b32_e32 v0, s2
	ds_read_b32 v2, v0
	ds_read_b32 v3, v0 offset:4
	ds_read_b32 v4, v0 offset:8
	ds_read_b32 v5, v0 offset:12
	v_readlane_b32 s2, v254, 8
	s_lshl_b32 s2, s2, 8
	v_readlane_b32 s4, v254, 6
	v_readlane_b32 s5, v254, 7
	s_add_u32 s2, s4, s2
	s_addc_u32 s3, s5, 0
	v_mov_b32_e32 v1, 0x1000
	v_mov_b32_e32 v6, 1
	global_atomic_add v1, v6, s[2:3] offset:1024
	s_waitcnt lgkmcnt(0)
	v_add_u32_e32 v6, 1, v4
	ds_write_b32 v0, v6 offset:8
	v_add_u32_e32 v4, 2, v4
	v_mul_lo_u32 v2, v2, v4
	v_mul_lo_u32 v3, v3, v4
	s_add_u32 s10, s86, 0x7400
	s_addc_u32 s11, s87, 0
	s_mov_b32 s4, 0x200000
	v_cmp_eq_u32_e32 vcc, 0, v5
	s_cbranch_vccnz .Lxb6_wait
